# G1 start skew: 32 distinct offsets per XCD, s_sleep 8 steps; v75 otherwise
# speedup vs baseline: 1.0033x; 1.0033x over previous
.LBB0_205:
	s_bfe_u32 s4, s2, 0x50003
	s_cmp_eq_u32 s4, 0
	s_cbranch_scc1 .Lskew_done_g1
.Lskew_loop_g1:
	s_sleep 8
	s_sub_u32 s4, s4, 1
	s_cmp_lg_u32 s4, 0
	s_cbranch_scc1 .Lskew_loop_g1
